# MLA: K/V^T tiles fetched HBM->LDS directly (global_load_lds_dwordx4, 3 pieces per wave per tile) instead of VGPR staging + ds_write
# speedup vs baseline: 1.0096x; 1.0096x over previous
; #define ATT_LSTORE(buf) do { LAS unsigned char* b_ = lds + (buf) * BUF; \
;         _Pragma("unroll") for (int i = 0; i < KPT; ++i) { if (KCH % NTHREADS == 0 || tid + i * NTHREADS < KCH) *(LAS u32x4*)(b_ + klo[i]) = kreg[i]; } \
;         _Pragma("unroll") for (int i = 0; i < VPT; ++i) *(LAS u32x4*)(b_ + vlo[i]) = vreg[i]; } while (0)
; template <int DQK, int DV, int FLAGS, int qp, int kp, int vts, int op> ...
;     ...
;     u32x4 kreg[KPT], vreg[VPT];
;     unsigned kgo[KPT], vgo[VPT], klo[KPT], vlo[VPT];
; #pragma unroll
;     for (int i = 0; i < KPT; ++i) { const int c = tid + i * NTHREADS; const int row = c / KC, cc = c % KC; kgo[i] = (unsigned)(row * kp + cc * 8) * 2u; klo[i] = (unsigned)(row * KROW + cc * 16); }
; #pragma unroll
;     for (int i = 0; i < VPT; ++i) { const int c = tid + i * NTHREADS; const int d = c >> 3, cc = c & 7; vgo[i] = (unsigned)(d * vts + cc * 8) * 2u; vlo[i] = (unsigned)(KT_BYTES + d * VROW + cc * 16); }
;     ...
;     ATT_GLOAD((FLAGS & AF_REV) ? kt_hi - 1 : kt_lo); ATT_LSTORE(0);
;     __syncthreads();
;     bool started = false;
;     const int prow = (r32 & ~12) | ((r32 & 4) << 1) | ((r32 & 8) >> 1);
;     const int ntile = kt_hi - kt_lo;
.LBB0_536:
	s_andn2_b64 vcc, exec, s[12:13]
	v_lshlrev_b32_e32 v170, 3, v19
	s_cbranch_vccnz .LBB0_524
	s_and_b32 s87, s19, 0xffffffe0
	s_add_i32 s16, s16, s17
	s_add_i32 s87, s87, s3
	s_lshl_b32 s15, s2, 2
	s_lshl_b32 s12, s16, 17
	s_or_b32 s88, s87, 31
	s_add_i32 s2, s15, 4
	s_bfe_u32 s17, s16, 0x30004
	s_and_b32 s12, s12, 0xe00000
	s_add_u32 s12, s14, s12
	s_addc_u32 s13, 0, 0
	s_add_u32 s12, s93, s12
	v_readlane_b32 s14, v252, 61
	v_mov_b32_e32 v21, v1
	s_addc_u32 s13, s14, s13
	s_mulk_i32 s17, 0xc0
	v_and_b32_e32 v22, 31, v17
	v_and_b32_e32 v19, 19, v17
	v_lshlrev_b32_e32 v23, 1, v17
	v_lshrrev_b32_e32 v17, 1, v17
	v_lshl_add_u64 v[176:177], s[12:13], 0, v[20:21]
	s_add_u32 s12, s18, s17
	v_and_b32_e32 v23, 8, v23
	v_and_b32_e32 v17, 4, v17
	s_addc_u32 s13, 0, 0
	v_readlane_b32 s14, v252, 63
	v_or3_b32 v17, v19, v23, v17
	s_add_u32 s12, s14, s12
	v_readlane_b32 s14, v253, 1
	v_mul_u32_u24_e32 v169, 0xd0, v17
	v_mul_u32_u24_e32 v171, 0x90, v22
	v_mov_b32_e32 v17, v1
	v_mov_b32_e32 v19, v1
	v_add_u32_e32 v22, s87, v22
	s_addc_u32 s13, s14, s13
	v_mov_b32_e32 v32, v1
	v_mov_b32_e32 v33, v1
	v_sub_u32_e32 v173, v22, v170
	v_lshl_add_u64 v[178:179], s[12:13], 0, v[16:17]
	v_lshl_add_u64 v[180:181], s[12:13], 0, v[18:19]
	v_mov_b32_e32 v34, v1
	v_mov_b32_e32 v35, v1
	v_mov_b32_e32 v36, v1
	v_mov_b32_e32 v37, v1
	v_mov_b32_e32 v38, v1
	v_mov_b32_e32 v39, v1
	v_mov_b32_e32 v40, v1
	v_mov_b32_e32 v41, v1
	v_mov_b32_e32 v42, v1
	v_mov_b32_e32 v43, v1
	v_mov_b32_e32 v44, v1
	v_mov_b32_e32 v45, v1
	v_mov_b32_e32 v46, v1
	v_mov_b32_e32 v47, v1
	v_mov_b32_e32 v183, 0
	v_mov_b64_e32 v[16:17], v[32:33]
	s_mov_b64 s[0:1], s[90:91]
	s_mov_b32 s3, 1
	s_xor_b32 s90, s15, -4
	s_mov_b64 s[82:83], 0
	s_mov_b32 s91, 63
	v_mov_b64_e32 v[18:19], v[34:35]
	v_mov_b64_e32 v[20:21], v[36:37]
	v_mov_b64_e32 v[22:23], v[38:39]
	v_mov_b64_e32 v[24:25], v[40:41]
	v_mov_b64_e32 v[26:27], v[42:43]
	v_mov_b64_e32 v[28:29], v[44:45]
	v_mov_b64_e32 v[30:31], v[46:47]
	v_mov_b32_e32 v175, 0
	v_mov_b32_e32 v48, 0
	v_mov_b32_e32 v49, v183
	v_mov_b32_e32 v50, v183
	v_mov_b32_e32 v51, v183
	v_mov_b32_e32 v52, v183
	v_mov_b32_e32 v53, v183
	v_mov_b32_e32 v54, v183
	v_mov_b32_e32 v55, v183
	v_mov_b32_e32 v56, v183
	v_mov_b32_e32 v57, v183
	v_mov_b32_e32 v58, v183
	v_mov_b32_e32 v59, v183
	v_mov_b32_e32 v60, v183
	v_mov_b32_e32 v61, v183
	v_mov_b32_e32 v62, v183
	v_mov_b32_e32 v63, v183
	s_andn2_b64 vcc, exec, s[4:5]
	s_cbranch_vccnz .Lq_fallback
	v_add_u32_e32 v187, v169, v0
	v_add_u32_e32 v213, 0xb000, v187
	v_add_u32_e32 v246, v171, v0
	v_add_u32_e32 v247, 0xb000, v246
	s_movk_i32 s16, 0x5800
	s_waitcnt vmcnt(0)
	v_add_u32_e32 v209, s16, v14
	v_add_u32_e32 v210, s16, v174
	v_add_u32_e32 v211, s16, v172
	ds_write_b128 v209, v[214:217]
	ds_write_b128 v210, v[222:225] offset:13312
	s_and_saveexec_b64 s[14:15], s[10:11]
	ds_write_b128 v211, v[218:221]
	s_or_b64 exec, exec, s[14:15]
	v_readfirstlane_b32 s12, v212
	s_lshr_b32 s12, s12, 6
	s_lshl_b32 s14, s12, 10
	s_cmp_ge_u32 s12, 6
	s_movk_i32 s15, 0x4000
	s_cselect_b32 s15, 0x2000, s15
	s_lshl_b32 s13, s12, 6
	s_mul_i32 s16, s13, 5462
	s_lshr_b32 s16, s16, 16
	s_mul_i32 vcc_lo, s16, 12
	s_sub_i32 vcc_lo, s13, vcc_lo
	s_mul_i32 s16, s16, 1536
	s_lshl_b32 vcc_lo, vcc_lo, 4
	s_add_i32 s16, s16, vcc_lo
	v_readfirstlane_b32 s98, v178
	v_readfirstlane_b32 s99, v179
	s_sub_u32 s98, s98, s16
	s_subb_u32 s99, s99, 0
	s_lshl_b32 s16, s12, 18
	v_readfirstlane_b32 s100, v176
	v_readfirstlane_b32 s101, v177
	s_sub_u32 s100, s100, s16
	s_subb_u32 s101, s101, 0
	v_and_b32_e32 v204, 63, v212
	s_add_i32 s13, s12, 0
	v_lshl_add_u32 v205, s13, 6, v204
	s_cmp_ge_u32 s13, 13
	s_movk_i32 s16, 5042
	s_cselect_b32 s16, 7282, s16
	s_cselect_b32 vcc_lo, 9, 13
	s_cselect_b32 vcc_hi, 7, 11
	s_movk_i32 m0, 0x600
	s_cselect_b32 m0, 0x8000, m0
	s_cselect_b32 s13, 832, 0
	s_nop 3
	v_subrev_u32_e32 v205, s13, v205
	v_mul_u32_u24_e32 v206, s16, v205
	v_lshrrev_b32_e32 v206, 16, v206
	v_mul_u32_u24_e32 v207, vcc_lo, v206
	v_sub_u32_e32 v207, v205, v207
	v_min_u32_e32 v207, vcc_hi, v207
	v_mul_u32_u24_e32 v206, m0, v206
	v_lshl_add_u32 v140, v207, 4, v206
	s_add_i32 s13, s12, 8
	v_lshl_add_u32 v205, s13, 6, v204
	s_cmp_ge_u32 s13, 13
	s_movk_i32 s16, 5042
	s_cselect_b32 s16, 7282, s16
	s_cselect_b32 vcc_lo, 9, 13
	s_cselect_b32 vcc_hi, 7, 11
	s_movk_i32 m0, 0x600
	s_cselect_b32 m0, 0x8000, m0
	s_cselect_b32 s13, 832, 0
	s_nop 3
	v_subrev_u32_e32 v205, s13, v205
	v_mul_u32_u24_e32 v206, s16, v205
	v_lshrrev_b32_e32 v206, 16, v206
	v_mul_u32_u24_e32 v207, vcc_lo, v206
	v_sub_u32_e32 v207, v205, v207
	v_min_u32_e32 v207, vcc_hi, v207
	v_mul_u32_u24_e32 v206, m0, v206
	v_lshl_add_u32 v141, v207, 4, v206
	s_lshr_b32 s13, s15, 10
	s_add_i32 s13, s13, s12
	v_lshl_add_u32 v205, s13, 6, v204
	s_cmp_ge_u32 s13, 13
	s_movk_i32 s16, 5042
	s_cselect_b32 s16, 7282, s16
	s_cselect_b32 vcc_lo, 9, 13
	s_cselect_b32 vcc_hi, 7, 11
	s_movk_i32 m0, 0x600
	s_cselect_b32 m0, 0x8000, m0
	s_cselect_b32 s13, 832, 0
	s_nop 3
	v_subrev_u32_e32 v205, s13, v205
	v_mul_u32_u24_e32 v206, s16, v205
	v_lshrrev_b32_e32 v206, 16, v206
	v_mul_u32_u24_e32 v207, vcc_lo, v206
	v_sub_u32_e32 v207, v205, v207
	v_min_u32_e32 v207, vcc_hi, v207
	v_mul_u32_u24_e32 v206, m0, v206
	v_lshl_add_u32 v142, v207, 4, v206
	s_add_u32 s98, s98, s96
	s_addc_u32 s99, s99, s97
	s_add_u32 s100, s100, 0x80
	s_addc_u32 s101, s101, 0
	s_add_i32 m0, s14, 0xb000
	s_nop 0
	global_load_lds_dwordx4 v140, s[98:99]
	s_cmp_ge_u32 s14, 0x1400
	s_cselect_b64 s[12:13], s[100:101], s[98:99]
	s_add_i32 m0, s14, 0xd000
	s_nop 0
	global_load_lds_dwordx4 v141, s[12:13]
	s_add_i32 s12, s14, s15
	s_add_i32 m0, s12, 0xb000
	s_nop 0
	global_load_lds_dwordx4 v142, s[100:101]
	s_add_u32 s98, s98, s96
	s_addc_u32 s99, s99, s97
	s_add_u32 s100, s100, 0x80
	s_addc_u32 s101, s101, 0
	s_lshr_b32 s20, s88, 6
	s_add_i32 s20, s20, 1
	s_min_i32 s20, s20, s2
	s_mov_b32 s3, 0
	s_waitcnt lgkmcnt(0)
	s_barrier
; #define LAS __attribute__((address_space(3)))
; template <int DQK, int DV, int FLAGS, int qp, int kp, int vts, int op> ...
;     ...
;             for (int c = 0; c < ND0 / 2; ++c) {
;                 if (c + 1 < ND0 / 2) {
; #pragma unroll
;                     for (int i = 0; i < 2; ++i) { kf[(c + 1) & 1][2 * i] = *(const LAS bf16x8*)(kb + (2 * c + 2 + i) * 32); kf[(c + 1) & 1][2 * i + 1] = *(const LAS bf16x8*)(kb + 32 * KROW + (2 * c + 2 + i) * 32); }
;                 }
; #pragma unroll
;                 for (int i = 0; i < 2; ++i) {
;                     p0 = __builtin_amdgcn_mfma_f32_32x32x16_bf16(kf[c & 1][2 * i], qr[2 * c + i], p0, 0, 0, 0);
;                     p1 = __builtin_amdgcn_mfma_f32_32x32x16_bf16(kf[c & 1][2 * i + 1], qr[2 * c + i], p1, 0, 0, 0);
;                 }
;                 __builtin_amdgcn_sched_barrier(0);
;             }
;             if (more) ATT_GLOAD((FLAGS & AF_REV) ? t - 1 : t + 1);
;     ...
;             f32x2 rs2 = {0.f, 0.f};
; #pragma unroll
;             for (int r = 0; r < 16; ++r) { p0[r] = __builtin_amdgcn_exp2f(p0[r]); p1[r] = __builtin_amdgcn_exp2f(p1[r]); }
; #pragma unroll
;             for (int r = 0; r < 16; r += 2) { rs2 += (f32x2){p0[r], p0[r + 1]}; rs2 += (f32x2){p1[r], p1[r + 1]}; }
;             l += rs2.x + rs2.y;
;             bf16x8 pf[4];
;             pf[0] = pack_bf16x8(p0, 0); pf[1] = pack_bf16x8(p0, 8); pf[2] = pack_bf16x8(p1, 0); pf[3] = pack_bf16x8(p1, 8);
;             __builtin_amdgcn_sched_barrier(0);
; #pragma unroll
;             for (int d = 0; d < NDB; ++d) {
;                 if (d + 1 < NDB) {
; #pragma unroll
;                     for (int ks = 0; ks < 4; ++ks) vf[(d + 1) & 1][ks] = *(const LAS bf16x8*)(vb + (d + 1) * 32 * VROW + ks * 32);
;                 }
; #pragma unroll
;                 for (int ks = 0; ks < 4; ++ks) o[d] = __builtin_amdgcn_mfma_f32_32x32x16_bf16(vf[d & 1][ks], pf[ks], o[d], 0, 0, 0);
;                 __builtin_amdgcn_sched_barrier(0);
;             }
	v_add_u32_e32 v206, v169, v0
	ds_read_b128 v[96:99], v206 offset:0
	ds_read_b128 v[104:107], v206 offset:6656
	ds_read_b128 v[100:103], v206 offset:32
	ds_read_b128 v[108:111], v206 offset:6688
	ds_read_b128 v[112:115], v206 offset:64
	ds_read_b128 v[120:123], v206 offset:6720
	ds_read_b128 v[116:119], v206 offset:96
	ds_read_b128 v[124:127], v206 offset:6752
	s_waitcnt lgkmcnt(4)
	v_mfma_f32_32x32x16_bf16 v[64:79], v[96:99], v[2:5], v[48:63]
	v_mfma_f32_32x32x16_bf16 v[80:95], v[104:107], v[2:5], v[48:63]
	v_mfma_f32_32x32x16_bf16 v[64:79], v[100:103], v[6:9], v[64:79]
	v_mfma_f32_32x32x16_bf16 v[80:95], v[108:111], v[6:9], v[80:95]
	ds_read_b128 v[96:99], v206 offset:128
	ds_read_b128 v[104:107], v206 offset:6784
	ds_read_b128 v[100:103], v206 offset:160
	ds_read_b128 v[108:111], v206 offset:6816
	s_waitcnt lgkmcnt(4)
	v_mfma_f32_32x32x16_bf16 v[64:79], v[112:115], v[10:13], v[64:79]
	v_mfma_f32_32x32x16_bf16 v[80:95], v[120:123], v[10:13], v[80:95]
	v_mfma_f32_32x32x16_bf16 v[64:79], v[116:119], v[128:131], v[64:79]
	v_mfma_f32_32x32x16_bf16 v[80:95], v[124:127], v[128:131], v[80:95]
	s_waitcnt lgkmcnt(0)
	v_mfma_f32_32x32x16_bf16 v[64:79], v[96:99], v[132:135], v[64:79]
	v_mfma_f32_32x32x16_bf16 v[80:95], v[104:107], v[132:135], v[80:95]
	v_mfma_f32_32x32x16_bf16 v[64:79], v[100:103], v[136:139], v[64:79]
	v_mfma_f32_32x32x16_bf16 v[80:95], v[108:111], v[136:139], v[80:95]
.Lq_top0:
	s_cmp_eq_u32 s3, 0
	s_cbranch_scc1 .Lq_gen0
	s_add_i32 s13, s3, 1
	s_cmp_ge_i32 s13, s20
	s_cbranch_scc1 .Lq_gen0
	ds_read_b128 v[96:99], v187 offset:22528
	ds_read_b128 v[104:107], v187 offset:29184
	ds_read_b128 v[100:103], v187 offset:22560
	ds_read_b128 v[108:111], v187 offset:29216
	ds_read_b128 v[112:115], v187 offset:22592
	ds_read_b128 v[120:123], v187 offset:29248
	ds_read_b128 v[116:119], v187 offset:22624
	ds_read_b128 v[124:127], v187 offset:29280
	v_mfma_f32_32x32x16_bf16 v[32:47], v[152:155], v[214:217], v[32:47]
	v_exp_f32_e32 v64, v64
	v_exp_f32_e32 v65, v65
	v_mfma_f32_32x32x16_bf16 v[16:31], v[188:191], v[214:217], v[16:31]
	v_exp_f32_e32 v80, v80
	v_exp_f32_e32 v81, v81
	v_add_f32_e32 v204, v64, v175
	v_mfma_f32_32x32x16_bf16 v[32:47], v[156:159], v[218:221], v[32:47]
	v_exp_f32_e32 v66, v66
	v_exp_f32_e32 v67, v67
	v_add_f32_e32 v204, v80, v204
	v_add_f32_e32 v205, v65, v81
	s_add_i32 s12, s3, 3
	s_cmp_ge_i32 s12, s2
	s_cbranch_scc1 .Lq_ng_s0
	s_add_i32 m0, s14, 0x10800
	s_nop 0
	global_load_lds_dwordx4 v140, s[98:99]
	s_cmp_ge_u32 s14, 0x1400
	s_cselect_b64 s[12:13], s[100:101], s[98:99]
	s_add_i32 m0, s14, 0x12800
	s_nop 0
	global_load_lds_dwordx4 v141, s[12:13]
	s_add_i32 s12, s14, s15
	s_add_i32 m0, s12, 0x10800
	s_nop 0
	global_load_lds_dwordx4 v142, s[100:101]
	s_add_u32 s98, s98, s96
	s_addc_u32 s99, s99, s97
	s_add_u32 s100, s100, 0x80
	s_addc_u32 s101, s101, 0
.Lq_ng_s0:
	v_mfma_f32_32x32x16_bf16 v[16:31], v[192:195], v[218:221], v[16:31]
	v_exp_f32_e32 v82, v82
	v_exp_f32_e32 v83, v83
	v_add_f32_e32 v204, v66, v204
	v_add_f32_e32 v205, v67, v205
	v_mfma_f32_32x32x16_bf16 v[32:47], v[160:163], v[222:225], v[32:47]
	v_exp_f32_e32 v68, v68
	v_exp_f32_e32 v69, v69
	v_add_f32_e32 v204, v82, v204
	v_add_f32_e32 v205, v83, v205
	v_mfma_f32_32x32x16_bf16 v[16:31], v[196:199], v[222:225], v[16:31]
	v_exp_f32_e32 v84, v84
	v_exp_f32_e32 v85, v85
	v_add_f32_e32 v204, v68, v204
	v_add_f32_e32 v205, v69, v205
	v_mfma_f32_32x32x16_bf16 v[32:47], v[164:167], v[226:229], v[32:47]
	v_exp_f32_e32 v70, v70
	v_exp_f32_e32 v71, v71
	v_add_f32_e32 v204, v84, v204
	v_add_f32_e32 v205, v85, v205
	v_mfma_f32_32x32x16_bf16 v[16:31], v[200:203], v[226:229], v[16:31]
	v_exp_f32_e32 v86, v86
	v_exp_f32_e32 v87, v87
	v_add_f32_e32 v204, v70, v204
	v_add_f32_e32 v205, v71, v205
	ds_read_b128 v[152:155], v246 offset:13312
	ds_read_b128 v[156:159], v246 offset:13344
	ds_read_b128 v[160:163], v246 offset:13376
	ds_read_b128 v[164:167], v246 offset:13408
	s_waitcnt lgkmcnt(8)
	v_mfma_f32_32x32x16_bf16 v[214:229], v[96:99], v[2:5], v[48:63]
	v_exp_f32_e32 v72, v72
	v_exp_f32_e32 v73, v73
	v_add_f32_e32 v204, v86, v204
	v_add_f32_e32 v205, v87, v205
	v_mfma_f32_32x32x16_bf16 v[230:245], v[104:107], v[2:5], v[48:63]
	v_exp_f32_e32 v88, v88
	v_exp_f32_e32 v89, v89
	v_add_f32_e32 v204, v72, v204
	v_add_f32_e32 v205, v73, v205
	v_mfma_f32_32x32x16_bf16 v[214:229], v[100:103], v[6:9], v[214:229]
	v_exp_f32_e32 v74, v74
	v_exp_f32_e32 v75, v75
	v_add_f32_e32 v204, v88, v204
	v_add_f32_e32 v205, v89, v205
	v_mfma_f32_32x32x16_bf16 v[230:245], v[108:111], v[6:9], v[230:245]
	v_exp_f32_e32 v90, v90
	v_exp_f32_e32 v91, v91
	v_add_f32_e32 v204, v74, v204
	v_add_f32_e32 v205, v75, v205
	ds_read_b128 v[96:99], v187 offset:22656
	ds_read_b128 v[104:107], v187 offset:29312
	ds_read_b128 v[100:103], v187 offset:22688
	ds_read_b128 v[108:111], v187 offset:29344
	s_waitcnt lgkmcnt(8)
	v_mfma_f32_32x32x16_bf16 v[214:229], v[112:115], v[10:13], v[214:229]
	v_exp_f32_e32 v76, v76
	v_exp_f32_e32 v77, v77
	v_add_f32_e32 v204, v90, v204
	v_add_f32_e32 v205, v91, v205
	v_mfma_f32_32x32x16_bf16 v[230:245], v[120:123], v[10:13], v[230:245]
	v_exp_f32_e32 v92, v92
	v_exp_f32_e32 v93, v93
	v_add_f32_e32 v204, v76, v204
	v_add_f32_e32 v205, v77, v205
	v_mfma_f32_32x32x16_bf16 v[214:229], v[116:119], v[128:131], v[214:229]
	v_exp_f32_e32 v78, v78
	v_exp_f32_e32 v79, v79
	v_add_f32_e32 v204, v92, v204
	v_add_f32_e32 v205, v93, v205
	v_mfma_f32_32x32x16_bf16 v[230:245], v[124:127], v[128:131], v[230:245]
	v_exp_f32_e32 v94, v94
	v_exp_f32_e32 v95, v95
	v_add_f32_e32 v204, v78, v204
	v_add_f32_e32 v205, v79, v205
	ds_read_b128 v[188:191], v246 offset:17920
	ds_read_b128 v[192:195], v246 offset:17952
	ds_read_b128 v[196:199], v246 offset:17984
	ds_read_b128 v[200:203], v246 offset:18016
	s_waitcnt lgkmcnt(4)
	v_mfma_f32_32x32x16_bf16 v[214:229], v[96:99], v[132:135], v[214:229]
	s_nop 0
	v_add_f32_e32 v204, v94, v204
	v_add_f32_e32 v205, v95, v205
	v_cvt_pk_bf16_f32 v64, v64, v65
	v_cvt_pk_bf16_f32 v65, v66, v67
	v_cvt_pk_bf16_f32 v66, v68, v69
	v_mfma_f32_32x32x16_bf16 v[230:245], v[104:107], v[132:135], v[230:245]
	v_cvt_pk_bf16_f32 v67, v70, v71
	v_cvt_pk_bf16_f32 v68, v72, v73
	v_cvt_pk_bf16_f32 v69, v74, v75
	v_cvt_pk_bf16_f32 v70, v76, v77
	v_cvt_pk_bf16_f32 v71, v78, v79
	v_mfma_f32_32x32x16_bf16 v[214:229], v[100:103], v[136:139], v[214:229]
	v_cvt_pk_bf16_f32 v72, v80, v81
	v_cvt_pk_bf16_f32 v73, v82, v83
	v_cvt_pk_bf16_f32 v74, v84, v85
	v_cvt_pk_bf16_f32 v75, v86, v87
	v_cvt_pk_bf16_f32 v76, v88, v89
	v_mfma_f32_32x32x16_bf16 v[230:245], v[108:111], v[136:139], v[230:245]
	v_cvt_pk_bf16_f32 v77, v90, v91
	v_cvt_pk_bf16_f32 v78, v92, v93
	v_cvt_pk_bf16_f32 v79, v94, v95
	v_add_f32_e32 v175, v204, v205
	s_branch .Lq_tailb0

; #define LAS __attribute__((address_space(3)))
; template <int DQK, int DV, int FLAGS, int qp, int kp, int vts, int op> ...
;     ...
;             for (int c = 0; c < ND0 / 2; ++c) {
;                 if (c + 1 < ND0 / 2) {
; #pragma unroll
;                     for (int i = 0; i < 2; ++i) { kf[(c + 1) & 1][2 * i] = *(const LAS bf16x8*)(kb + (2 * c + 2 + i) * 32); kf[(c + 1) & 1][2 * i + 1] = *(const LAS bf16x8*)(kb + 32 * KROW + (2 * c + 2 + i) * 32); }
;                 }
; #pragma unroll
;                 for (int i = 0; i < 2; ++i) {
;                     p0 = __builtin_amdgcn_mfma_f32_32x32x16_bf16(kf[c & 1][2 * i], qr[2 * c + i], p0, 0, 0, 0);
;                     p1 = __builtin_amdgcn_mfma_f32_32x32x16_bf16(kf[c & 1][2 * i + 1], qr[2 * c + i], p1, 0, 0, 0);
;                 }
;                 __builtin_amdgcn_sched_barrier(0);
;             }
;             if (more) ATT_GLOAD((FLAGS & AF_REV) ? t - 1 : t + 1);
;     ...
;             for (int r = 0; r < 16; ++r) { p0[r] = __builtin_amdgcn_exp2f(p0[r]); p1[r] = __builtin_amdgcn_exp2f(p1[r]); }
; #pragma unroll
;             for (int r = 0; r < 16; r += 2) { rs2 += (f32x2){p0[r], p0[r + 1]}; rs2 += (f32x2){p1[r], p1[r + 1]}; }
;             l += rs2.x + rs2.y;
;             bf16x8 pf[4];
;             pf[0] = pack_bf16x8(p0, 0); pf[1] = pack_bf16x8(p0, 8); pf[2] = pack_bf16x8(p1, 0); pf[3] = pack_bf16x8(p1, 8);
;             __builtin_amdgcn_sched_barrier(0);
; #pragma unroll
;             for (int d = 0; d < NDB; ++d) {
;                 if (d + 1 < NDB) {
; #pragma unroll
;                     for (int ks = 0; ks < 4; ++ks) vf[(d + 1) & 1][ks] = *(const LAS bf16x8*)(vb + (d + 1) * 32 * VROW + ks * 32);
;                 }
; #pragma unroll
;                 for (int ks = 0; ks < 4; ++ks) o[d] = __builtin_amdgcn_mfma_f32_32x32x16_bf16(vf[d & 1][ks], pf[ks], o[d], 0, 0, 0);
;                 __builtin_amdgcn_sched_barrier(0);
;             }
;         }
;         if (skip && more) ATT_GLOAD((FLAGS & AF_REV) ? t - 1 : t + 1);
;         if (more) ATT_LSTORE(cur ^ 1);
;         __syncthreads();
.Lq_noqk_q0:
.Lq_tail0:
	s_add_i32 s12, s3, 3
	s_cmp_ge_i32 s12, s2
	s_cbranch_scc1 .Lq_nols_q0
	s_and_b32 s16, s12, 3
	s_mulk_i32 s16, 0x5800
	s_add_i32 m0, s14, s16
	s_nop 0
	global_load_lds_dwordx4 v140, s[98:99]
	s_cmp_ge_u32 s14, 0x1400
	s_cselect_b64 s[12:13], s[100:101], s[98:99]
	s_add_i32 m0, s14, s16
	s_add_i32 m0, m0, 0x2000
	s_nop 0
	global_load_lds_dwordx4 v141, s[12:13]
	s_add_i32 s12, s14, s15
	s_add_i32 m0, s12, s16
	s_nop 0
	global_load_lds_dwordx4 v142, s[100:101]
	s_add_u32 s98, s98, s96
	s_addc_u32 s99, s99, s97
	s_add_u32 s100, s100, 0x80
	s_addc_u32 s101, s101, 0
.Lq_nols_q0:
.Lq_tailb0:
	s_add_i32 s12, s3, 3
	s_cmp_ge_i32 s12, s2
	s_cbranch_scc1 .Lq_w0_0
	s_waitcnt vmcnt(3)
	s_branch .Lq_wd_0
.Lq_w0_0:
	s_waitcnt vmcnt(0)
.Lq_wd_0:
	s_add_i32 s3, s3, 1
	s_cmp_ge_i32 s3, s2
	s_cbranch_scc1 .Lq_flush1
	s_waitcnt lgkmcnt(0)
	s_barrier
.Lq_top1:
	s_cmp_eq_u32 s3, 0
	s_cbranch_scc1 .Lq_gen1
	s_add_i32 s13, s3, 1
	s_cmp_ge_i32 s13, s20
	s_cbranch_scc1 .Lq_gen1
	ds_read_b128 v[96:99], v213 offset:0
	ds_read_b128 v[104:107], v213 offset:6656
	ds_read_b128 v[100:103], v213 offset:32
	ds_read_b128 v[108:111], v213 offset:6688
	ds_read_b128 v[112:115], v213 offset:64
	ds_read_b128 v[120:123], v213 offset:6720
	ds_read_b128 v[116:119], v213 offset:96
	ds_read_b128 v[124:127], v213 offset:6752
	v_mfma_f32_32x32x16_bf16 v[32:47], v[152:155], v[64:67], v[32:47]
	v_exp_f32_e32 v214, v214
	v_exp_f32_e32 v215, v215
	v_mfma_f32_32x32x16_bf16 v[16:31], v[188:191], v[64:67], v[16:31]
	v_exp_f32_e32 v230, v230
	v_exp_f32_e32 v231, v231
	v_add_f32_e32 v204, v214, v175
	v_mfma_f32_32x32x16_bf16 v[32:47], v[156:159], v[68:71], v[32:47]
	v_exp_f32_e32 v216, v216
	v_exp_f32_e32 v217, v217
	v_add_f32_e32 v204, v230, v204
	v_add_f32_e32 v205, v215, v231
	s_add_i32 s12, s3, 3
	s_cmp_ge_i32 s12, s2
	s_cbranch_scc1 .Lq_ng_s1
	s_add_i32 m0, s14, 0x0
	s_nop 0
	global_load_lds_dwordx4 v140, s[98:99]
	s_cmp_ge_u32 s14, 0x1400
	s_cselect_b64 s[12:13], s[100:101], s[98:99]
	s_add_i32 m0, s14, 0x2000
	s_nop 0
	global_load_lds_dwordx4 v141, s[12:13]
	s_add_i32 s12, s14, s15
	s_add_i32 m0, s12, 0x0
	s_nop 0
	global_load_lds_dwordx4 v142, s[100:101]
	s_add_u32 s98, s98, s96
	s_addc_u32 s99, s99, s97
	s_add_u32 s100, s100, 0x80
	s_addc_u32 s101, s101, 0
.Lq_ng_s1:
	v_mfma_f32_32x32x16_bf16 v[16:31], v[192:195], v[68:71], v[16:31]
	v_exp_f32_e32 v232, v232
	v_exp_f32_e32 v233, v233
	v_add_f32_e32 v204, v216, v204
	v_add_f32_e32 v205, v217, v205
	v_mfma_f32_32x32x16_bf16 v[32:47], v[160:163], v[72:75], v[32:47]
	v_exp_f32_e32 v218, v218
	v_exp_f32_e32 v219, v219
	v_add_f32_e32 v204, v232, v204
	v_add_f32_e32 v205, v233, v205
	v_mfma_f32_32x32x16_bf16 v[16:31], v[196:199], v[72:75], v[16:31]
	v_exp_f32_e32 v234, v234
	v_exp_f32_e32 v235, v235
	v_add_f32_e32 v204, v218, v204
	v_add_f32_e32 v205, v219, v205
	v_mfma_f32_32x32x16_bf16 v[32:47], v[164:167], v[76:79], v[32:47]
	v_exp_f32_e32 v220, v220
	v_exp_f32_e32 v221, v221
	v_add_f32_e32 v204, v234, v204
	v_add_f32_e32 v205, v235, v205
	v_mfma_f32_32x32x16_bf16 v[16:31], v[200:203], v[76:79], v[16:31]
	v_exp_f32_e32 v236, v236
	v_exp_f32_e32 v237, v237
	v_add_f32_e32 v204, v220, v204
	v_add_f32_e32 v205, v221, v205
	ds_read_b128 v[152:155], v246 offset:35840
	ds_read_b128 v[156:159], v246 offset:35872
	ds_read_b128 v[160:163], v246 offset:35904
	ds_read_b128 v[164:167], v246 offset:35936
	s_waitcnt lgkmcnt(8)
	v_mfma_f32_32x32x16_bf16 v[64:79], v[96:99], v[2:5], v[48:63]
	v_exp_f32_e32 v222, v222
	v_exp_f32_e32 v223, v223
	v_add_f32_e32 v204, v236, v204
	v_add_f32_e32 v205, v237, v205
	v_mfma_f32_32x32x16_bf16 v[80:95], v[104:107], v[2:5], v[48:63]
	v_exp_f32_e32 v238, v238
	v_exp_f32_e32 v239, v239
	v_add_f32_e32 v204, v222, v204
	v_add_f32_e32 v205, v223, v205
	v_mfma_f32_32x32x16_bf16 v[64:79], v[100:103], v[6:9], v[64:79]
	v_exp_f32_e32 v224, v224
	v_exp_f32_e32 v225, v225
	v_add_f32_e32 v204, v238, v204
	v_add_f32_e32 v205, v239, v205
	v_mfma_f32_32x32x16_bf16 v[80:95], v[108:111], v[6:9], v[80:95]
	v_exp_f32_e32 v240, v240
	v_exp_f32_e32 v241, v241
	v_add_f32_e32 v204, v224, v204
	v_add_f32_e32 v205, v225, v205
	ds_read_b128 v[96:99], v213 offset:128
	ds_read_b128 v[104:107], v213 offset:6784
	ds_read_b128 v[100:103], v213 offset:160
	ds_read_b128 v[108:111], v213 offset:6816
	s_waitcnt lgkmcnt(8)
	v_mfma_f32_32x32x16_bf16 v[64:79], v[112:115], v[10:13], v[64:79]
	v_exp_f32_e32 v226, v226
	v_exp_f32_e32 v227, v227
	v_add_f32_e32 v204, v240, v204
	v_add_f32_e32 v205, v241, v205
	v_mfma_f32_32x32x16_bf16 v[80:95], v[120:123], v[10:13], v[80:95]
	v_exp_f32_e32 v242, v242
	v_exp_f32_e32 v243, v243
	v_add_f32_e32 v204, v226, v204
	v_add_f32_e32 v205, v227, v205
	v_mfma_f32_32x32x16_bf16 v[64:79], v[116:119], v[128:131], v[64:79]
	v_exp_f32_e32 v228, v228
	v_exp_f32_e32 v229, v229
	v_add_f32_e32 v204, v242, v204
	v_add_f32_e32 v205, v243, v205
	v_mfma_f32_32x32x16_bf16 v[80:95], v[124:127], v[128:131], v[80:95]
	v_exp_f32_e32 v244, v244
	v_exp_f32_e32 v245, v245
	v_add_f32_e32 v204, v228, v204
	v_add_f32_e32 v205, v229, v205
	ds_read_b128 v[188:191], v246 offset:40448
	ds_read_b128 v[192:195], v246 offset:40480
	ds_read_b128 v[196:199], v246 offset:40512
	ds_read_b128 v[200:203], v246 offset:40544
	s_waitcnt lgkmcnt(4)
	v_mfma_f32_32x32x16_bf16 v[64:79], v[96:99], v[132:135], v[64:79]
	s_nop 0
	v_add_f32_e32 v204, v244, v204
	v_add_f32_e32 v205, v245, v205
	v_cvt_pk_bf16_f32 v214, v214, v215
	v_cvt_pk_bf16_f32 v215, v216, v217
	v_cvt_pk_bf16_f32 v216, v218, v219
	v_mfma_f32_32x32x16_bf16 v[80:95], v[104:107], v[132:135], v[80:95]
	v_cvt_pk_bf16_f32 v217, v220, v221
	v_cvt_pk_bf16_f32 v218, v222, v223
	v_cvt_pk_bf16_f32 v219, v224, v225
	v_cvt_pk_bf16_f32 v220, v226, v227
	v_cvt_pk_bf16_f32 v221, v228, v229
	v_mfma_f32_32x32x16_bf16 v[64:79], v[100:103], v[136:139], v[64:79]
	v_cvt_pk_bf16_f32 v222, v230, v231
	v_cvt_pk_bf16_f32 v223, v232, v233
	v_cvt_pk_bf16_f32 v224, v234, v235
	v_cvt_pk_bf16_f32 v225, v236, v237
	v_cvt_pk_bf16_f32 v226, v238, v239
	v_mfma_f32_32x32x16_bf16 v[80:95], v[108:111], v[136:139], v[80:95]
	v_cvt_pk_bf16_f32 v227, v240, v241
	v_cvt_pk_bf16_f32 v228, v242, v243
	v_cvt_pk_bf16_f32 v229, v244, v245
	v_add_f32_e32 v175, v204, v205
	s_branch .Lq_tailb1

; #define LAS __attribute__((address_space(3)))
; template <int DQK, int DV, int FLAGS, int qp, int kp, int vts, int op> ...
;     ...
;             for (int c = 0; c < ND0 / 2; ++c) {
;                 if (c + 1 < ND0 / 2) {
; #pragma unroll
;                     for (int i = 0; i < 2; ++i) { kf[(c + 1) & 1][2 * i] = *(const LAS bf16x8*)(kb + (2 * c + 2 + i) * 32); kf[(c + 1) & 1][2 * i + 1] = *(const LAS bf16x8*)(kb + 32 * KROW + (2 * c + 2 + i) * 32); }
;                 }
; #pragma unroll
;                 for (int i = 0; i < 2; ++i) {
;                     p0 = __builtin_amdgcn_mfma_f32_32x32x16_bf16(kf[c & 1][2 * i], qr[2 * c + i], p0, 0, 0, 0);
;                     p1 = __builtin_amdgcn_mfma_f32_32x32x16_bf16(kf[c & 1][2 * i + 1], qr[2 * c + i], p1, 0, 0, 0);
;                 }
;                 __builtin_amdgcn_sched_barrier(0);
;             }
;             if (more) ATT_GLOAD((FLAGS & AF_REV) ? t - 1 : t + 1);
;     ...
;             for (int r = 0; r < 16; ++r) { p0[r] = __builtin_amdgcn_exp2f(p0[r]); p1[r] = __builtin_amdgcn_exp2f(p1[r]); }
; #pragma unroll
;             for (int r = 0; r < 16; r += 2) { rs2 += (f32x2){p0[r], p0[r + 1]}; rs2 += (f32x2){p1[r], p1[r + 1]}; }
;             l += rs2.x + rs2.y;
;             bf16x8 pf[4];
;             pf[0] = pack_bf16x8(p0, 0); pf[1] = pack_bf16x8(p0, 8); pf[2] = pack_bf16x8(p1, 0); pf[3] = pack_bf16x8(p1, 8);
;             __builtin_amdgcn_sched_barrier(0);
; #pragma unroll
;             for (int d = 0; d < NDB; ++d) {
;                 if (d + 1 < NDB) {
; #pragma unroll
;                     for (int ks = 0; ks < 4; ++ks) vf[(d + 1) & 1][ks] = *(const LAS bf16x8*)(vb + (d + 1) * 32 * VROW + ks * 32);
;                 }
; #pragma unroll
;                 for (int ks = 0; ks < 4; ++ks) o[d] = __builtin_amdgcn_mfma_f32_32x32x16_bf16(vf[d & 1][ks], pf[ks], o[d], 0, 0, 0);
;                 __builtin_amdgcn_sched_barrier(0);
;             }
;         }
;         if (skip && more) ATT_GLOAD((FLAGS & AF_REV) ? t - 1 : t + 1);
;         if (more) ATT_LSTORE(cur ^ 1);
;         __syncthreads();
.Lq_w0_1:
	s_waitcnt vmcnt(0)
.Lq_wd_1:
	s_add_i32 s3, s3, 1
	s_cmp_ge_i32 s3, s2
	s_cbranch_scc1 .Lq_flush0
	s_waitcnt lgkmcnt(0)
	s_barrier
.Lq_top2:
	s_cmp_eq_u32 s3, 0
	s_cbranch_scc1 .Lq_gen2
	s_add_i32 s13, s3, 1
	s_cmp_ge_i32 s13, s20
	s_cbranch_scc1 .Lq_gen2
	ds_read_b128 v[96:99], v213 offset:22528
	ds_read_b128 v[104:107], v213 offset:29184
	ds_read_b128 v[100:103], v213 offset:22560
	ds_read_b128 v[108:111], v213 offset:29216
	ds_read_b128 v[112:115], v213 offset:22592
	ds_read_b128 v[120:123], v213 offset:29248
	ds_read_b128 v[116:119], v213 offset:22624
	ds_read_b128 v[124:127], v213 offset:29280
	v_mfma_f32_32x32x16_bf16 v[32:47], v[152:155], v[214:217], v[32:47]
	v_exp_f32_e32 v64, v64
	v_exp_f32_e32 v65, v65
	v_mfma_f32_32x32x16_bf16 v[16:31], v[188:191], v[214:217], v[16:31]
	v_exp_f32_e32 v80, v80
	v_exp_f32_e32 v81, v81
	v_add_f32_e32 v204, v64, v175
	v_mfma_f32_32x32x16_bf16 v[32:47], v[156:159], v[218:221], v[32:47]
	v_exp_f32_e32 v66, v66
	v_exp_f32_e32 v67, v67
	v_add_f32_e32 v204, v80, v204
	v_add_f32_e32 v205, v65, v81
	s_add_i32 s12, s3, 3
	s_cmp_ge_i32 s12, s2
	s_cbranch_scc1 .Lq_ng_s2
	s_add_i32 m0, s14, 0x5800
	s_nop 0
	global_load_lds_dwordx4 v140, s[98:99]
	s_cmp_ge_u32 s14, 0x1400
	s_cselect_b64 s[12:13], s[100:101], s[98:99]
	s_add_i32 m0, s14, 0x7800
	s_nop 0
	global_load_lds_dwordx4 v141, s[12:13]
	s_add_i32 s12, s14, s15
	s_add_i32 m0, s12, 0x5800
	s_nop 0
	global_load_lds_dwordx4 v142, s[100:101]
	s_add_u32 s98, s98, s96
	s_addc_u32 s99, s99, s97
	s_add_u32 s100, s100, 0x80
	s_addc_u32 s101, s101, 0
.Lq_ng_s2:
	v_mfma_f32_32x32x16_bf16 v[16:31], v[192:195], v[218:221], v[16:31]
	v_exp_f32_e32 v82, v82
	v_exp_f32_e32 v83, v83
	v_add_f32_e32 v204, v66, v204
	v_add_f32_e32 v205, v67, v205
	v_mfma_f32_32x32x16_bf16 v[32:47], v[160:163], v[222:225], v[32:47]
	v_exp_f32_e32 v68, v68
	v_exp_f32_e32 v69, v69
	v_add_f32_e32 v204, v82, v204
	v_add_f32_e32 v205, v83, v205
	v_mfma_f32_32x32x16_bf16 v[16:31], v[196:199], v[222:225], v[16:31]
	v_exp_f32_e32 v84, v84
	v_exp_f32_e32 v85, v85
	v_add_f32_e32 v204, v68, v204
	v_add_f32_e32 v205, v69, v205
	v_mfma_f32_32x32x16_bf16 v[32:47], v[164:167], v[226:229], v[32:47]
	v_exp_f32_e32 v70, v70
	v_exp_f32_e32 v71, v71
	v_add_f32_e32 v204, v84, v204
	v_add_f32_e32 v205, v85, v205
	v_mfma_f32_32x32x16_bf16 v[16:31], v[200:203], v[226:229], v[16:31]
	v_exp_f32_e32 v86, v86
	v_exp_f32_e32 v87, v87
	v_add_f32_e32 v204, v70, v204
	v_add_f32_e32 v205, v71, v205
	ds_read_b128 v[152:155], v247 offset:13312
	ds_read_b128 v[156:159], v247 offset:13344
	ds_read_b128 v[160:163], v247 offset:13376
	ds_read_b128 v[164:167], v247 offset:13408
	s_waitcnt lgkmcnt(8)
	v_mfma_f32_32x32x16_bf16 v[214:229], v[96:99], v[2:5], v[48:63]
	v_exp_f32_e32 v72, v72
	v_exp_f32_e32 v73, v73
	v_add_f32_e32 v204, v86, v204
	v_add_f32_e32 v205, v87, v205
	v_mfma_f32_32x32x16_bf16 v[230:245], v[104:107], v[2:5], v[48:63]
	v_exp_f32_e32 v88, v88
	v_exp_f32_e32 v89, v89
	v_add_f32_e32 v204, v72, v204
	v_add_f32_e32 v205, v73, v205
	v_mfma_f32_32x32x16_bf16 v[214:229], v[100:103], v[6:9], v[214:229]
	v_exp_f32_e32 v74, v74
	v_exp_f32_e32 v75, v75
	v_add_f32_e32 v204, v88, v204
	v_add_f32_e32 v205, v89, v205
	v_mfma_f32_32x32x16_bf16 v[230:245], v[108:111], v[6:9], v[230:245]
	v_exp_f32_e32 v90, v90
	v_exp_f32_e32 v91, v91
	v_add_f32_e32 v204, v74, v204
	v_add_f32_e32 v205, v75, v205
	ds_read_b128 v[96:99], v213 offset:22656
	ds_read_b128 v[104:107], v213 offset:29312
	ds_read_b128 v[100:103], v213 offset:22688
	ds_read_b128 v[108:111], v213 offset:29344
	s_waitcnt lgkmcnt(8)
	v_mfma_f32_32x32x16_bf16 v[214:229], v[112:115], v[10:13], v[214:229]
	v_exp_f32_e32 v76, v76
	v_exp_f32_e32 v77, v77
	v_add_f32_e32 v204, v90, v204
	v_add_f32_e32 v205, v91, v205
	v_mfma_f32_32x32x16_bf16 v[230:245], v[120:123], v[10:13], v[230:245]
	v_exp_f32_e32 v92, v92
	v_exp_f32_e32 v93, v93
	v_add_f32_e32 v204, v76, v204
	v_add_f32_e32 v205, v77, v205
	v_mfma_f32_32x32x16_bf16 v[214:229], v[116:119], v[128:131], v[214:229]
	v_exp_f32_e32 v78, v78
	v_exp_f32_e32 v79, v79
	v_add_f32_e32 v204, v92, v204
	v_add_f32_e32 v205, v93, v205
	v_mfma_f32_32x32x16_bf16 v[230:245], v[124:127], v[128:131], v[230:245]
	v_exp_f32_e32 v94, v94
	v_exp_f32_e32 v95, v95
	v_add_f32_e32 v204, v78, v204
	v_add_f32_e32 v205, v79, v205
	ds_read_b128 v[188:191], v247 offset:17920
	ds_read_b128 v[192:195], v247 offset:17952
	ds_read_b128 v[196:199], v247 offset:17984
	ds_read_b128 v[200:203], v247 offset:18016
	s_waitcnt lgkmcnt(4)
	v_mfma_f32_32x32x16_bf16 v[214:229], v[96:99], v[132:135], v[214:229]
	s_nop 0
	v_add_f32_e32 v204, v94, v204
	v_add_f32_e32 v205, v95, v205
	v_cvt_pk_bf16_f32 v64, v64, v65
	v_cvt_pk_bf16_f32 v65, v66, v67
	v_cvt_pk_bf16_f32 v66, v68, v69
	v_mfma_f32_32x32x16_bf16 v[230:245], v[104:107], v[132:135], v[230:245]
	v_cvt_pk_bf16_f32 v67, v70, v71
	v_cvt_pk_bf16_f32 v68, v72, v73
	v_cvt_pk_bf16_f32 v69, v74, v75
	v_cvt_pk_bf16_f32 v70, v76, v77
	v_cvt_pk_bf16_f32 v71, v78, v79
	v_mfma_f32_32x32x16_bf16 v[214:229], v[100:103], v[136:139], v[214:229]
	v_cvt_pk_bf16_f32 v72, v80, v81
	v_cvt_pk_bf16_f32 v73, v82, v83
	v_cvt_pk_bf16_f32 v74, v84, v85
	v_cvt_pk_bf16_f32 v75, v86, v87
	v_cvt_pk_bf16_f32 v76, v88, v89
	v_mfma_f32_32x32x16_bf16 v[230:245], v[108:111], v[136:139], v[230:245]
	v_cvt_pk_bf16_f32 v77, v90, v91
	v_cvt_pk_bf16_f32 v78, v92, v93
	v_cvt_pk_bf16_f32 v79, v94, v95
	v_add_f32_e32 v175, v204, v205
	s_branch .Lq_tailb2

; #define LAS __attribute__((address_space(3)))
; template <int DQK, int DV, int FLAGS, int qp, int kp, int vts, int op> ...
;     ...
;             for (int c = 0; c < ND0 / 2; ++c) {
;                 if (c + 1 < ND0 / 2) {
; #pragma unroll
;                     for (int i = 0; i < 2; ++i) { kf[(c + 1) & 1][2 * i] = *(const LAS bf16x8*)(kb + (2 * c + 2 + i) * 32); kf[(c + 1) & 1][2 * i + 1] = *(const LAS bf16x8*)(kb + 32 * KROW + (2 * c + 2 + i) * 32); }
;                 }
; #pragma unroll
;                 for (int i = 0; i < 2; ++i) {
;                     p0 = __builtin_amdgcn_mfma_f32_32x32x16_bf16(kf[c & 1][2 * i], qr[2 * c + i], p0, 0, 0, 0);
;                     p1 = __builtin_amdgcn_mfma_f32_32x32x16_bf16(kf[c & 1][2 * i + 1], qr[2 * c + i], p1, 0, 0, 0);
;                 }
;                 __builtin_amdgcn_sched_barrier(0);
;             }
;             if (more) ATT_GLOAD((FLAGS & AF_REV) ? t - 1 : t + 1);
;     ...
;             for (int r = 0; r < 16; ++r) { p0[r] = __builtin_amdgcn_exp2f(p0[r]); p1[r] = __builtin_amdgcn_exp2f(p1[r]); }
; #pragma unroll
;             for (int r = 0; r < 16; r += 2) { rs2 += (f32x2){p0[r], p0[r + 1]}; rs2 += (f32x2){p1[r], p1[r + 1]}; }
;             l += rs2.x + rs2.y;
;             bf16x8 pf[4];
;             pf[0] = pack_bf16x8(p0, 0); pf[1] = pack_bf16x8(p0, 8); pf[2] = pack_bf16x8(p1, 0); pf[3] = pack_bf16x8(p1, 8);
;             __builtin_amdgcn_sched_barrier(0);
; #pragma unroll
;             for (int d = 0; d < NDB; ++d) {
;                 if (d + 1 < NDB) {
; #pragma unroll
;                     for (int ks = 0; ks < 4; ++ks) vf[(d + 1) & 1][ks] = *(const LAS bf16x8*)(vb + (d + 1) * 32 * VROW + ks * 32);
;                 }
; #pragma unroll
;                 for (int ks = 0; ks < 4; ++ks) o[d] = __builtin_amdgcn_mfma_f32_32x32x16_bf16(vf[d & 1][ks], pf[ks], o[d], 0, 0, 0);
;                 __builtin_amdgcn_sched_barrier(0);
;             }
;         }
;         if (skip && more) ATT_GLOAD((FLAGS & AF_REV) ? t - 1 : t + 1);
;         if (more) ATT_LSTORE(cur ^ 1);
;         __syncthreads();
.Lq_w0_2:
	s_waitcnt vmcnt(0)
.Lq_wd_2:
	s_add_i32 s3, s3, 1
	s_cmp_ge_i32 s3, s2
	s_cbranch_scc1 .Lq_flush1
	s_waitcnt lgkmcnt(0)
	s_barrier
.Lq_top3:
	s_cmp_eq_u32 s3, 0
	s_cbranch_scc1 .Lq_gen3
	s_add_i32 s13, s3, 1
	s_cmp_ge_i32 s13, s20
	s_cbranch_scc1 .Lq_gen3
	ds_read_b128 v[96:99], v187 offset:0
	ds_read_b128 v[104:107], v187 offset:6656
	ds_read_b128 v[100:103], v187 offset:32
	ds_read_b128 v[108:111], v187 offset:6688
	ds_read_b128 v[112:115], v187 offset:64
	ds_read_b128 v[120:123], v187 offset:6720
	ds_read_b128 v[116:119], v187 offset:96
	ds_read_b128 v[124:127], v187 offset:6752
	v_mfma_f32_32x32x16_bf16 v[32:47], v[152:155], v[64:67], v[32:47]
	v_exp_f32_e32 v214, v214
	v_exp_f32_e32 v215, v215
	v_mfma_f32_32x32x16_bf16 v[16:31], v[188:191], v[64:67], v[16:31]
	v_exp_f32_e32 v230, v230
	v_exp_f32_e32 v231, v231
	v_add_f32_e32 v204, v214, v175
	v_mfma_f32_32x32x16_bf16 v[32:47], v[156:159], v[68:71], v[32:47]
	v_exp_f32_e32 v216, v216
	v_exp_f32_e32 v217, v217
	v_add_f32_e32 v204, v230, v204
	v_add_f32_e32 v205, v215, v231
	s_add_i32 s12, s3, 3
	s_cmp_ge_i32 s12, s2
	s_cbranch_scc1 .Lq_ng_s3
	s_add_i32 m0, s14, 0xb000
	s_nop 0
	global_load_lds_dwordx4 v140, s[98:99]
	s_cmp_ge_u32 s14, 0x1400
	s_cselect_b64 s[12:13], s[100:101], s[98:99]
	s_add_i32 m0, s14, 0xd000
	s_nop 0
	global_load_lds_dwordx4 v141, s[12:13]
	s_add_i32 s12, s14, s15
	s_add_i32 m0, s12, 0xb000
	s_nop 0
	global_load_lds_dwordx4 v142, s[100:101]
	s_add_u32 s98, s98, s96
	s_addc_u32 s99, s99, s97
	s_add_u32 s100, s100, 0x80
	s_addc_u32 s101, s101, 0
.Lq_ng_s3:
	v_mfma_f32_32x32x16_bf16 v[16:31], v[192:195], v[68:71], v[16:31]
	v_exp_f32_e32 v232, v232
	v_exp_f32_e32 v233, v233
	v_add_f32_e32 v204, v216, v204
	v_add_f32_e32 v205, v217, v205
	v_mfma_f32_32x32x16_bf16 v[32:47], v[160:163], v[72:75], v[32:47]
	v_exp_f32_e32 v218, v218
	v_exp_f32_e32 v219, v219
	v_add_f32_e32 v204, v232, v204
	v_add_f32_e32 v205, v233, v205
	v_mfma_f32_32x32x16_bf16 v[16:31], v[196:199], v[72:75], v[16:31]
	v_exp_f32_e32 v234, v234
	v_exp_f32_e32 v235, v235
	v_add_f32_e32 v204, v218, v204
	v_add_f32_e32 v205, v219, v205
	v_mfma_f32_32x32x16_bf16 v[32:47], v[164:167], v[76:79], v[32:47]
	v_exp_f32_e32 v220, v220
	v_exp_f32_e32 v221, v221
	v_add_f32_e32 v204, v234, v204
	v_add_f32_e32 v205, v235, v205
	v_mfma_f32_32x32x16_bf16 v[16:31], v[200:203], v[76:79], v[16:31]
	v_exp_f32_e32 v236, v236
	v_exp_f32_e32 v237, v237
	v_add_f32_e32 v204, v220, v204
	v_add_f32_e32 v205, v221, v205
	ds_read_b128 v[152:155], v247 offset:35840
	ds_read_b128 v[156:159], v247 offset:35872
	ds_read_b128 v[160:163], v247 offset:35904
	ds_read_b128 v[164:167], v247 offset:35936
	s_waitcnt lgkmcnt(8)
	v_mfma_f32_32x32x16_bf16 v[64:79], v[96:99], v[2:5], v[48:63]
	v_exp_f32_e32 v222, v222
	v_exp_f32_e32 v223, v223
	v_add_f32_e32 v204, v236, v204
	v_add_f32_e32 v205, v237, v205
	v_mfma_f32_32x32x16_bf16 v[80:95], v[104:107], v[2:5], v[48:63]
	v_exp_f32_e32 v238, v238
	v_exp_f32_e32 v239, v239
	v_add_f32_e32 v204, v222, v204
	v_add_f32_e32 v205, v223, v205
	v_mfma_f32_32x32x16_bf16 v[64:79], v[100:103], v[6:9], v[64:79]
	v_exp_f32_e32 v224, v224
	v_exp_f32_e32 v225, v225
	v_add_f32_e32 v204, v238, v204
	v_add_f32_e32 v205, v239, v205
	v_mfma_f32_32x32x16_bf16 v[80:95], v[108:111], v[6:9], v[80:95]
	v_exp_f32_e32 v240, v240
	v_exp_f32_e32 v241, v241
	v_add_f32_e32 v204, v224, v204
	v_add_f32_e32 v205, v225, v205
	ds_read_b128 v[96:99], v187 offset:128
	ds_read_b128 v[104:107], v187 offset:6784
	ds_read_b128 v[100:103], v187 offset:160
	ds_read_b128 v[108:111], v187 offset:6816
	s_waitcnt lgkmcnt(8)
	v_mfma_f32_32x32x16_bf16 v[64:79], v[112:115], v[10:13], v[64:79]
	v_exp_f32_e32 v226, v226
	v_exp_f32_e32 v227, v227
	v_add_f32_e32 v204, v240, v204
	v_add_f32_e32 v205, v241, v205
	v_mfma_f32_32x32x16_bf16 v[80:95], v[120:123], v[10:13], v[80:95]
	v_exp_f32_e32 v242, v242
	v_exp_f32_e32 v243, v243
	v_add_f32_e32 v204, v226, v204
	v_add_f32_e32 v205, v227, v205
	v_mfma_f32_32x32x16_bf16 v[64:79], v[116:119], v[128:131], v[64:79]
	v_exp_f32_e32 v228, v228
	v_exp_f32_e32 v229, v229
	v_add_f32_e32 v204, v242, v204
	v_add_f32_e32 v205, v243, v205
	v_mfma_f32_32x32x16_bf16 v[80:95], v[124:127], v[128:131], v[80:95]
	v_exp_f32_e32 v244, v244
	v_exp_f32_e32 v245, v245
	v_add_f32_e32 v204, v228, v204
	v_add_f32_e32 v205, v229, v205
	ds_read_b128 v[188:191], v247 offset:40448
	ds_read_b128 v[192:195], v247 offset:40480
	ds_read_b128 v[196:199], v247 offset:40512
	ds_read_b128 v[200:203], v247 offset:40544
	s_waitcnt lgkmcnt(4)
	v_mfma_f32_32x32x16_bf16 v[64:79], v[96:99], v[132:135], v[64:79]
	s_nop 0
	v_add_f32_e32 v204, v244, v204
	v_add_f32_e32 v205, v245, v205
	v_cvt_pk_bf16_f32 v214, v214, v215
	v_cvt_pk_bf16_f32 v215, v216, v217
	v_cvt_pk_bf16_f32 v216, v218, v219
	v_mfma_f32_32x32x16_bf16 v[80:95], v[104:107], v[132:135], v[80:95]
	v_cvt_pk_bf16_f32 v217, v220, v221
	v_cvt_pk_bf16_f32 v218, v222, v223
	v_cvt_pk_bf16_f32 v219, v224, v225
	v_cvt_pk_bf16_f32 v220, v226, v227
	v_cvt_pk_bf16_f32 v221, v228, v229
	v_mfma_f32_32x32x16_bf16 v[64:79], v[100:103], v[136:139], v[64:79]
	v_cvt_pk_bf16_f32 v222, v230, v231
	v_cvt_pk_bf16_f32 v223, v232, v233
	v_cvt_pk_bf16_f32 v224, v234, v235
	v_cvt_pk_bf16_f32 v225, v236, v237
	v_cvt_pk_bf16_f32 v226, v238, v239
	v_mfma_f32_32x32x16_bf16 v[80:95], v[108:111], v[136:139], v[80:95]
	v_cvt_pk_bf16_f32 v227, v240, v241
	v_cvt_pk_bf16_f32 v228, v242, v243
	v_cvt_pk_bf16_f32 v229, v244, v245
	v_add_f32_e32 v175, v204, v205
	s_branch .Lq_tailb3

; __device__ __forceinline__ float shfl_xor_l(float v, int o, int lane) { return __builtin_bit_cast(float, __builtin_amdgcn_ds_bpermute((lane ^ o) << 2, __builtin_bit_cast(int, v))); }
; #define ATT_LSTORE(buf) do { LAS unsigned char* b_ = lds + (buf) * BUF; \
;         _Pragma("unroll") for (int i = 0; i < KPT; ++i) { if (KCH % NTHREADS == 0 || tid + i * NTHREADS < KCH) *(LAS u32x4*)(b_ + klo[i]) = kreg[i]; } \
;         _Pragma("unroll") for (int i = 0; i < VPT; ++i) *(LAS u32x4*)(b_ + vlo[i]) = vreg[i]; } while (0)
; template <int DQK, int DV, int FLAGS, int qp, int kp, int vts, int op> ...
;     ...
;         if (skip && more) ATT_GLOAD((FLAGS & AF_REV) ? t - 1 : t + 1);
;         if (more) ATT_LSTORE(cur ^ 1);
;         __syncthreads();
;     }
;     ...
;     float lt = l + shfl_xor_l(l, 32, lane);
.Lq_w0_3:
	s_waitcnt vmcnt(0)
.Lq_wd_3:
	s_add_i32 s3, s3, 1
	s_cmp_ge_i32 s3, s2
	s_cbranch_scc1 .Lq_flush0
	s_waitcnt lgkmcnt(0)
	s_barrier
	s_branch .Lq_top0
.Lq_flush0:
	s_waitcnt vmcnt(0)
	s_cmp_lt_i32 s20, s2
	s_cbranch_scc1 .LBB0_572
	s_waitcnt lgkmcnt(0)
	v_mfma_f32_32x32x16_bf16 v[32:47], v[152:155], v[214:217], v[32:47]
	v_mfma_f32_32x32x16_bf16 v[16:31], v[188:191], v[214:217], v[16:31]
	v_mfma_f32_32x32x16_bf16 v[32:47], v[156:159], v[218:221], v[32:47]
	v_mfma_f32_32x32x16_bf16 v[16:31], v[192:195], v[218:221], v[16:31]
	v_mfma_f32_32x32x16_bf16 v[32:47], v[160:163], v[222:225], v[32:47]
	v_mfma_f32_32x32x16_bf16 v[16:31], v[196:199], v[222:225], v[16:31]
	v_mfma_f32_32x32x16_bf16 v[32:47], v[164:167], v[226:229], v[32:47]
	v_mfma_f32_32x32x16_bf16 v[16:31], v[200:203], v[226:229], v[16:31]
	s_branch .LBB0_572
.Lq_flush1:
	s_waitcnt vmcnt(0)
	s_cmp_lt_i32 s20, s2
	s_cbranch_scc1 .LBB0_572
	s_waitcnt lgkmcnt(0)
	v_mfma_f32_32x32x16_bf16 v[32:47], v[152:155], v[64:67], v[32:47]
	v_mfma_f32_32x32x16_bf16 v[16:31], v[188:191], v[64:67], v[16:31]
	v_mfma_f32_32x32x16_bf16 v[32:47], v[156:159], v[68:71], v[32:47]
	v_mfma_f32_32x32x16_bf16 v[16:31], v[192:195], v[68:71], v[16:31]
	v_mfma_f32_32x32x16_bf16 v[32:47], v[160:163], v[72:75], v[32:47]
	v_mfma_f32_32x32x16_bf16 v[16:31], v[196:199], v[72:75], v[16:31]
	v_mfma_f32_32x32x16_bf16 v[32:47], v[164:167], v[76:79], v[32:47]
	v_mfma_f32_32x32x16_bf16 v[16:31], v[200:203], v[76:79], v[16:31]
	s_branch .LBB0_572
